# census batching with two pad instructions so the code after the first barrier keeps its 64-byte placement
# baseline (speedup 1.0000x reference)
; __device__ __forceinline__ unsigned xb_ld(unsigned* p)              { return __hip_atomic_load(p, __ATOMIC_RELAXED, __HIP_MEMORY_SCOPE_AGENT); }
; #define G opq(gridDim.x)
; #define c opq(blockIdx.x)
; __device__ __forceinline__ void xcd_barrier_complete(unsigned* bar, unsigned x, unsigned& nloc, unsigned& nx) {
;     ...
;     for (;;) {
;         sum = 0u; cnt = 0u; mine = 0u;
; #pragma unroll
;         for (unsigned j = 0; j < 16; ++j) { const unsigned c = xb_ld(&bar[XB_XCNT(j)]); sum += c; cnt += (c > 0u) ? 1u : 0u; mine = (j == x) ? c : mine; }
;         if (sum == G) break;
;         __builtin_amdgcn_s_sleep(1);
;         if ((++sp & 255u) == 0u) { if (xb_ld(&bar[XB_TMO])) break; if (sp > XB_SPIN_CAP) { atomicAdd(&bar[XB_TMO], 1u); break; } }
;     }
;     nloc = mine > 0u ? mine : 1u; nx = cnt > 0u ? cnt : 1u;
.LBB0_87:
	v_readlane_b32 s4, v254, 3
	v_readlane_b32 s5, v254, 4
	global_load_dword v2, v16, s[86:87] sc1
	s_waitcnt lgkmcnt(0)
	global_load_dword v0, v16, s[88:89] sc1
	global_load_dword v1, v16, s[56:57] sc1
	s_mov_b64 s[8:9], -1
	s_nop 0
	s_nop 0
	global_load_dword v3, v16, s[4:5] sc1
	v_readlane_b32 s4, v254, 5
	v_readlane_b32 s5, v254, 6
	s_nop 0
	s_nop 0
	s_nop 0
	s_nop 0
	s_nop 0
	global_load_dword v4, v16, s[4:5] sc1
	v_readlane_b32 s4, v254, 7
	v_readlane_b32 s5, v254, 8
	s_nop 0
	s_nop 0
	s_nop 2
	global_load_dword v5, v16, s[4:5] sc1
	v_readlane_b32 s4, v254, 9
	v_readlane_b32 s5, v254, 10
	s_nop 0
	s_nop 0
	s_nop 2
	global_load_dword v6, v16, s[4:5] sc1
	v_readlane_b32 s4, v254, 11
	v_readlane_b32 s5, v254, 12
	s_nop 0
	s_nop 0
	s_nop 2
	global_load_dword v7, v16, s[4:5] sc1
	v_readlane_b32 s4, v254, 13
	v_readlane_b32 s5, v254, 14
	s_nop 0
	s_nop 0
	s_nop 2
	global_load_dword v8, v16, s[4:5] sc1
	v_readlane_b32 s4, v254, 15
	v_readlane_b32 s5, v254, 16
	s_nop 0
	s_nop 0
	s_nop 2
	global_load_dword v9, v16, s[4:5] sc1
	v_readlane_b32 s4, v254, 17
	v_readlane_b32 s5, v254, 18
	s_nop 0
	s_nop 0
	s_nop 2
	global_load_dword v10, v16, s[4:5] sc1
	v_readlane_b32 s4, v254, 19
	v_readlane_b32 s5, v254, 20
	s_nop 0
	s_nop 0
	s_nop 2
	global_load_dword v11, v16, s[4:5] sc1
	v_readlane_b32 s4, v254, 21
	v_readlane_b32 s5, v254, 22
	s_nop 0
	s_nop 0
	s_nop 2
	global_load_dword v12, v16, s[4:5] sc1
	v_readlane_b32 s4, v254, 23
	v_readlane_b32 s5, v254, 24
	s_nop 0
	s_nop 0
	s_nop 2
	global_load_dword v13, v16, s[4:5] sc1
	v_readlane_b32 s4, v254, 25
	v_readlane_b32 s5, v254, 26
	s_nop 0
	s_nop 0
	s_nop 2
	global_load_dword v14, v16, s[4:5] sc1
	v_readlane_b32 s4, v254, 27
	v_readlane_b32 s5, v254, 28
	s_nop 0
	s_nop 0
	s_nop 2
	global_load_dword v15, v16, s[4:5] sc1
	s_mov_b64 s[4:5], -1
	s_waitcnt vmcnt(0)
	v_add_u32_e32 v17, v0, v2
	v_add_u32_e32 v17, v17, v1
	v_add_u32_e32 v17, v17, v3
	v_add_u32_e32 v17, v17, v4
	v_add_u32_e32 v17, v17, v5
	v_add_u32_e32 v17, v17, v6
	v_add_u32_e32 v17, v17, v7
	v_add_u32_e32 v17, v17, v8
	v_add_u32_e32 v17, v17, v9
	v_add_u32_e32 v17, v17, v10
	v_add_u32_e32 v17, v17, v11
	v_add_u32_e32 v17, v17, v12
	v_add_u32_e32 v17, v17, v13
	v_add_u32_e32 v17, v17, v14
	v_add_u32_e32 v17, v17, v15
	s_nop 0
	s_nop 0
	v_cmp_eq_u32_e32 vcc, s20, v17
	s_cbranch_vccnz .LBB0_86
	s_and_b32 s1, s0, 0xff
	s_cmp_eq_u32 s1, 0
	s_mov_b64 s[10:11], -1
	s_sleep 1
	s_cbranch_scc1 .LBB0_91
	s_and_b64 vcc, exec, s[10:11]
	s_cbranch_vccz .LBB0_86
